# sc1 (write-through) on the SwiGLU epilogue stores of the 4 FFN-in GEMM phases only
# speedup vs baseline: 1.0088x; 1.0024x over previous
; #define EPI_LOOP_ROWS _Pragma("unroll") for (int ai = 0; ai < 2; ++ai) _Pragma("unroll") for (int m = 0; m < 4; ++m)
; DI u32x4 pack8(const f32x4 a, const f32x4 b) { return (u32x4){pack2(a[0], a[1]), pack2(a[2], a[3]), pack2(b[0], b[1]), pack2(b[2], b[3])}; }
; DI float silu_f(float x) { return x * __builtin_amdgcn_rcpf(1.f + __expf(-x)); }
;     DI void operator()(const AccT& acc, int brow, int bcol, int wr, int wc, int fr, int fq) const {
;         const int col = (bcol >> 1) + wc * 32 + fq * 8;
;         EPI_LOOP_ROWS { const size_t row = brow + ai * 128 + wr * 64 + m * 16 + fr; f32x4 o[2];
; #pragma unroll
;             for (int n = 0; n < 2; ++n) { const f32x4 g = acc[ai][0][m][n], u = acc[ai][1][m][n];
; #pragma unroll
;                 for (int j = 0; j < 4; ++j) o[n][j] = silu_f(g[j]) * u[j]; }
;             *(u32x4*)(ACT + row * DFF + col) = pack8(o[0], o[1]); }
;     }
.LBB0_766:
	v_mov_b32_e32 v144, v252
	s_ashr_i32 s9, s34, 1
	v_lshrrev_b32_e32 v146, 1, v144
	v_and_b32_e32 v147, 0x60, v146
	v_and_b32_e32 v146, 24, v146
	v_add3_u32 v146, v147, s9, v146
	v_mul_f32_e32 v147, 0xbfb8aa3b, v124
	v_exp_f32_e32 v147, v147
	v_mul_f32_e32 v148, 0xbfb8aa3b, v125
	v_exp_f32_e32 v149, v148
	v_and_b32_e32 v145, 15, v144
	v_add_f32_e32 v147, 1.0, v147
	v_rcp_f32_e32 v148, v147
	v_add_f32_e32 v147, 1.0, v149
	v_rcp_f32_e32 v149, v147
	v_ashrrev_i32_e32 v144, 2, v144
	v_and_b32_e32 v144, 0xffffffc0, v144
	v_add3_u32 v144, v145, s30, v144
	v_pk_mul_f32 v[124:125], v[124:125], v[148:149]
	v_mul_f32_e32 v145, 0xbfb8aa3b, v126
	v_mul_f32_e32 v148, 0xbfb8aa3b, v127
	v_exp_f32_e32 v145, v145
	v_exp_f32_e32 v148, v148
	v_pk_mul_f32 v[116:117], v[124:125], v[116:117]
	v_ashrrev_i32_e32 v147, 31, v146
	v_add_f32_e32 v124, 1.0, v145
	v_add_f32_e32 v125, 1.0, v148
	v_mul_f32_e32 v145, 0xbfb8aa3b, v120
	v_rcp_f32_e32 v124, v124
	v_rcp_f32_e32 v125, v125
	v_exp_f32_e32 v145, v145
	v_mul_f32_e32 v148, 0xbfb8aa3b, v121
	v_exp_f32_e32 v148, v148
	v_pk_mul_f32 v[124:125], v[126:127], v[124:125]
	v_add_f32_e32 v126, 1.0, v145
	v_mul_f32_e32 v145, 0xbfb8aa3b, v122
	v_add_f32_e32 v127, 1.0, v148
	v_exp_f32_e32 v145, v145
	v_mul_f32_e32 v148, 0xbfb8aa3b, v123
	v_exp_f32_e32 v149, v148
	v_rcp_f32_e32 v126, v126
	v_add_f32_e32 v145, 1.0, v145
	v_rcp_f32_e32 v127, v127
	v_rcp_f32_e32 v148, v145
	v_add_f32_e32 v145, 1.0, v149
	v_rcp_f32_e32 v149, v145
	v_pk_mul_f32 v[120:121], v[120:121], v[126:127]
	v_pk_mul_f32 v[118:119], v[124:125], v[118:119]
	v_pk_mul_f32 v[112:113], v[120:121], v[112:113]
	v_pk_mul_f32 v[120:121], v[122:123], v[148:149]
	v_cvt_pk_bf16_f32 v116, v116, v117
	v_pk_mul_f32 v[114:115], v[120:121], v[114:115]
	v_cvt_pk_bf16_f32 v117, v118, v119
	v_cvt_pk_bf16_f32 v119, v114, v115
	v_mul_f32_e32 v114, 0xbfb8aa3b, v108
	v_exp_f32_e32 v122, v114
	v_mul_f32_e32 v114, 0xbfb8aa3b, v109
	v_exp_f32_e32 v123, v114
	v_cvt_pk_bf16_f32 v118, v112, v113
	v_mov_b64_e32 v[112:113], s[96:97]
	v_mad_i64_i32 v[120:121], s[14:15], v144, s47, v[112:113]
	v_lshlrev_b64 v[114:115], 1, v[146:147]
	v_add_f32_e32 v122, 1.0, v122
	v_add_f32_e32 v123, 1.0, v123
	v_lshl_add_u64 v[120:121], v[120:121], 0, v[114:115]
	v_rcp_f32_e32 v122, v122
	v_rcp_f32_e32 v123, v123
	global_store_dwordx4 v[120:121], v[116:119], off sc1
	s_andn2_b64 vcc, exec, s[6:7]
	s_mov_b64 s[6:7], -1
	v_mul_f32_e32 v116, 0xbfb8aa3b, v110
	v_mul_f32_e32 v117, 0xbfb8aa3b, v111
	v_exp_f32_e32 v116, v116
	v_exp_f32_e32 v117, v117
	v_pk_mul_f32 v[108:109], v[108:109], v[122:123]
	v_add_u32_e32 v118, 16, v144
	v_pk_mul_f32 v[100:101], v[108:109], v[100:101]
	v_add_f32_e32 v108, 1.0, v116
	v_add_f32_e32 v109, 1.0, v117
	v_mul_f32_e32 v116, 0xbfb8aa3b, v104
	v_mul_f32_e32 v117, 0xbfb8aa3b, v105
	v_rcp_f32_e32 v108, v108
	v_rcp_f32_e32 v109, v109
	v_exp_f32_e32 v116, v116
	v_exp_f32_e32 v117, v117
	v_pk_mul_f32 v[108:109], v[110:111], v[108:109]
	v_add_f32_e32 v110, 1.0, v116
	v_add_f32_e32 v111, 1.0, v117
	v_mul_f32_e32 v116, 0xbfb8aa3b, v106
	v_mul_f32_e32 v117, 0xbfb8aa3b, v107
	v_exp_f32_e32 v116, v116
	v_exp_f32_e32 v117, v117
	v_rcp_f32_e32 v110, v110
	v_rcp_f32_e32 v111, v111
	v_add_f32_e32 v116, 1.0, v116
	v_add_f32_e32 v117, 1.0, v117
	v_rcp_f32_e32 v116, v116
	v_rcp_f32_e32 v117, v117
	v_pk_mul_f32 v[104:105], v[104:105], v[110:111]
	v_pk_mul_f32 v[102:103], v[108:109], v[102:103]
	v_pk_mul_f32 v[104:105], v[104:105], v[96:97]
	v_pk_mul_f32 v[96:97], v[106:107], v[116:117]
	s_nop 0
	v_pk_mul_f32 v[106:107], v[96:97], v[98:99]
	v_cvt_pk_bf16_f32 v96, v100, v101
	v_mul_f32_e32 v100, 0xbfb8aa3b, v92
	v_cvt_pk_bf16_f32 v97, v102, v103
	v_exp_f32_e32 v102, v100
	v_mul_f32_e32 v100, 0xbfb8aa3b, v93
	v_exp_f32_e32 v103, v100
	v_mad_i64_i32 v[100:101], s[14:15], v118, s47, v[112:113]
	v_cvt_pk_bf16_f32 v98, v104, v105
	v_cvt_pk_bf16_f32 v99, v106, v107
	v_add_f32_e32 v102, 1.0, v102
	v_add_f32_e32 v103, 1.0, v103
	v_lshl_add_u64 v[100:101], v[100:101], 0, v[114:115]
	v_rcp_f32_e32 v102, v102
	v_rcp_f32_e32 v103, v103
	global_store_dwordx4 v[100:101], v[96:99], off sc1
	v_pk_mul_f32 v[92:93], v[92:93], v[102:103]
	s_nop 0
	v_mul_f32_e32 v96, 0xbfb8aa3b, v94
	v_mul_f32_e32 v97, 0xbfb8aa3b, v95
	v_exp_f32_e32 v96, v96
	v_exp_f32_e32 v97, v97
	v_pk_mul_f32 v[84:85], v[92:93], v[84:85]
	v_add_u32_e32 v98, 32, v144
	v_add_f32_e32 v92, 1.0, v96
	v_add_f32_e32 v93, 1.0, v97
	v_mul_f32_e32 v96, 0xbfb8aa3b, v88
	v_mul_f32_e32 v97, 0xbfb8aa3b, v89
	v_rcp_f32_e32 v92, v92
	v_rcp_f32_e32 v93, v93
	v_exp_f32_e32 v96, v96
	v_exp_f32_e32 v97, v97
	v_pk_mul_f32 v[92:93], v[94:95], v[92:93]
	v_add_f32_e32 v94, 1.0, v96
	v_add_f32_e32 v95, 1.0, v97
	v_mul_f32_e32 v96, 0xbfb8aa3b, v90
	v_mul_f32_e32 v97, 0xbfb8aa3b, v91
	v_exp_f32_e32 v96, v96
	v_exp_f32_e32 v97, v97
	v_rcp_f32_e32 v94, v94
	v_rcp_f32_e32 v95, v95
	v_add_f32_e32 v96, 1.0, v96
	v_add_f32_e32 v97, 1.0, v97
	v_rcp_f32_e32 v96, v96
	v_rcp_f32_e32 v97, v97
	v_pk_mul_f32 v[88:89], v[88:89], v[94:95]
	v_pk_mul_f32 v[86:87], v[92:93], v[86:87]
	v_pk_mul_f32 v[88:89], v[88:89], v[80:81]
	v_pk_mul_f32 v[80:81], v[90:91], v[96:97]
	s_nop 0
	v_pk_mul_f32 v[90:91], v[80:81], v[82:83]
	v_cvt_pk_bf16_f32 v80, v84, v85
	v_mul_f32_e32 v84, 0xbfb8aa3b, v76
	v_cvt_pk_bf16_f32 v81, v86, v87
	v_exp_f32_e32 v86, v84
	v_mul_f32_e32 v84, 0xbfb8aa3b, v77
	v_exp_f32_e32 v87, v84
	v_mad_i64_i32 v[84:85], s[14:15], v98, s47, v[112:113]
	v_cvt_pk_bf16_f32 v82, v88, v89
	v_cvt_pk_bf16_f32 v83, v90, v91
	v_add_f32_e32 v86, 1.0, v86
	v_add_f32_e32 v87, 1.0, v87
	v_lshl_add_u64 v[84:85], v[84:85], 0, v[114:115]
	v_rcp_f32_e32 v86, v86
	v_rcp_f32_e32 v87, v87
; #define EPI_LOOP_ROWS _Pragma("unroll") for (int ai = 0; ai < 2; ++ai) _Pragma("unroll") for (int m = 0; m < 4; ++m)
; DI u32x4 pack8(const f32x4 a, const f32x4 b) { return (u32x4){pack2(a[0], a[1]), pack2(a[2], a[3]), pack2(b[0], b[1]), pack2(b[2], b[3])}; }
; DI float silu_f(float x) { return x * __builtin_amdgcn_rcpf(1.f + __expf(-x)); }
;     DI void operator()(const AccT& acc, int brow, int bcol, int wr, int wc, int fr, int fq) const {
;     ...
;         EPI_LOOP_ROWS { const size_t row = brow + ai * 128 + wr * 64 + m * 16 + fr; f32x4 o[2];
; #pragma unroll
;             for (int n = 0; n < 2; ++n) { const f32x4 g = acc[ai][0][m][n], u = acc[ai][1][m][n];
; #pragma unroll
;                 for (int j = 0; j < 4; ++j) o[n][j] = silu_f(g[j]) * u[j]; }
;             *(u32x4*)(ACT + row * DFF + col) = pack8(o[0], o[1]); }
	global_store_dwordx4 v[84:85], v[80:83], off sc1
	v_pk_mul_f32 v[76:77], v[76:77], v[86:87]
	s_nop 0
	v_mul_f32_e32 v80, 0xbfb8aa3b, v78
	v_mul_f32_e32 v81, 0xbfb8aa3b, v79
	v_exp_f32_e32 v80, v80
	v_exp_f32_e32 v81, v81
	v_pk_mul_f32 v[68:69], v[76:77], v[68:69]
	v_add_u32_e32 v82, 48, v144
	v_add_f32_e32 v76, 1.0, v80
	v_add_f32_e32 v77, 1.0, v81
	v_mul_f32_e32 v80, 0xbfb8aa3b, v72
	v_mul_f32_e32 v81, 0xbfb8aa3b, v73
	v_rcp_f32_e32 v76, v76
	v_rcp_f32_e32 v77, v77
	v_exp_f32_e32 v80, v80
	v_exp_f32_e32 v81, v81
	v_pk_mul_f32 v[76:77], v[78:79], v[76:77]
	v_add_f32_e32 v78, 1.0, v80
	v_add_f32_e32 v79, 1.0, v81
	v_mul_f32_e32 v80, 0xbfb8aa3b, v74
	v_mul_f32_e32 v81, 0xbfb8aa3b, v75
	v_exp_f32_e32 v80, v80
	v_exp_f32_e32 v81, v81
	v_rcp_f32_e32 v78, v78
	v_rcp_f32_e32 v79, v79
	v_add_f32_e32 v80, 1.0, v80
	v_add_f32_e32 v81, 1.0, v81
	v_rcp_f32_e32 v80, v80
	v_rcp_f32_e32 v81, v81
	v_pk_mul_f32 v[72:73], v[72:73], v[78:79]
	v_pk_mul_f32 v[70:71], v[76:77], v[70:71]
	v_pk_mul_f32 v[72:73], v[72:73], v[64:65]
	v_pk_mul_f32 v[64:65], v[74:75], v[80:81]
	s_nop 0
	v_pk_mul_f32 v[74:75], v[64:65], v[66:67]
	v_cvt_pk_bf16_f32 v64, v68, v69
	v_mul_f32_e32 v68, 0xbfb8aa3b, v60
	v_cvt_pk_bf16_f32 v65, v70, v71
	v_exp_f32_e32 v70, v68
	v_mul_f32_e32 v68, 0xbfb8aa3b, v61
	v_exp_f32_e32 v71, v68
	v_mad_i64_i32 v[68:69], s[14:15], v82, s47, v[112:113]
	v_cvt_pk_bf16_f32 v66, v72, v73
	v_cvt_pk_bf16_f32 v67, v74, v75
	v_add_f32_e32 v70, 1.0, v70
	v_add_f32_e32 v71, 1.0, v71
	v_lshl_add_u64 v[68:69], v[68:69], 0, v[114:115]
	v_rcp_f32_e32 v70, v70
	v_rcp_f32_e32 v71, v71
	global_store_dwordx4 v[68:69], v[64:67], off sc1
	v_pk_mul_f32 v[60:61], v[60:61], v[70:71]
	s_nop 0
	v_mul_f32_e32 v64, 0xbfb8aa3b, v62
	v_mul_f32_e32 v65, 0xbfb8aa3b, v63
	v_exp_f32_e32 v64, v64
	v_exp_f32_e32 v65, v65
	v_pk_mul_f32 v[52:53], v[60:61], v[52:53]
	v_add_u32_e32 v66, 0x80, v144
	v_add_f32_e32 v60, 1.0, v64
	v_add_f32_e32 v61, 1.0, v65
	v_mul_f32_e32 v64, 0xbfb8aa3b, v56
	v_mul_f32_e32 v65, 0xbfb8aa3b, v57
	v_rcp_f32_e32 v60, v60
	v_rcp_f32_e32 v61, v61
	v_exp_f32_e32 v64, v64
	v_exp_f32_e32 v65, v65
	v_pk_mul_f32 v[60:61], v[62:63], v[60:61]
	v_add_f32_e32 v62, 1.0, v64
	v_add_f32_e32 v63, 1.0, v65
	v_mul_f32_e32 v64, 0xbfb8aa3b, v58
	v_mul_f32_e32 v65, 0xbfb8aa3b, v59
	v_exp_f32_e32 v64, v64
	v_exp_f32_e32 v65, v65
	v_rcp_f32_e32 v62, v62
	v_rcp_f32_e32 v63, v63
	v_add_f32_e32 v64, 1.0, v64
	v_add_f32_e32 v65, 1.0, v65
	v_rcp_f32_e32 v64, v64
	v_rcp_f32_e32 v65, v65
	v_pk_mul_f32 v[56:57], v[56:57], v[62:63]
	v_pk_mul_f32 v[54:55], v[60:61], v[54:55]
	v_pk_mul_f32 v[56:57], v[56:57], v[48:49]
	v_pk_mul_f32 v[48:49], v[58:59], v[64:65]
	s_nop 0
	v_pk_mul_f32 v[58:59], v[48:49], v[50:51]
	v_cvt_pk_bf16_f32 v48, v52, v53
	v_mul_f32_e32 v52, 0xbfb8aa3b, v44
	v_cvt_pk_bf16_f32 v49, v54, v55
	v_exp_f32_e32 v54, v52
	v_mul_f32_e32 v52, 0xbfb8aa3b, v45
	v_exp_f32_e32 v55, v52
	v_mad_i64_i32 v[52:53], s[14:15], v66, s47, v[112:113]
	v_cvt_pk_bf16_f32 v50, v56, v57
	v_cvt_pk_bf16_f32 v51, v58, v59
	v_add_f32_e32 v54, 1.0, v54
	v_add_f32_e32 v55, 1.0, v55
	v_lshl_add_u64 v[52:53], v[52:53], 0, v[114:115]
	v_rcp_f32_e32 v54, v54
	v_rcp_f32_e32 v55, v55
	global_store_dwordx4 v[52:53], v[48:51], off sc1
	v_pk_mul_f32 v[44:45], v[44:45], v[54:55]
	s_nop 0
	v_mul_f32_e32 v48, 0xbfb8aa3b, v46
	v_mul_f32_e32 v49, 0xbfb8aa3b, v47
	v_exp_f32_e32 v48, v48
	v_exp_f32_e32 v49, v49
	v_pk_mul_f32 v[36:37], v[44:45], v[36:37]
	v_add_u32_e32 v50, 0x90, v144
	v_add_f32_e32 v44, 1.0, v48
	v_add_f32_e32 v45, 1.0, v49
	v_mul_f32_e32 v48, 0xbfb8aa3b, v40
	v_mul_f32_e32 v49, 0xbfb8aa3b, v41
	v_rcp_f32_e32 v44, v44
	v_rcp_f32_e32 v45, v45
	v_exp_f32_e32 v48, v48
	v_exp_f32_e32 v49, v49
	v_pk_mul_f32 v[44:45], v[46:47], v[44:45]
	v_add_f32_e32 v46, 1.0, v48
	v_add_f32_e32 v47, 1.0, v49
	v_mul_f32_e32 v48, 0xbfb8aa3b, v42
	v_mul_f32_e32 v49, 0xbfb8aa3b, v43
	v_exp_f32_e32 v48, v48
	v_exp_f32_e32 v49, v49
; DI float silu_f(float x) { return x * __builtin_amdgcn_rcpf(1.f + __expf(-x)); }
; #define BAR __builtin_amdgcn_s_barrier()
; #define EPI_LOOP_ROWS _Pragma("unroll") for (int ai = 0; ai < 2; ++ai) _Pragma("unroll") for (int m = 0; m < 4; ++m)
; DI u32x4 pack8(const f32x4 a, const f32x4 b) { return (u32x4){pack2(a[0], a[1]), pack2(a[2], a[3]), pack2(b[0], b[1]), pack2(b[2], b[3])}; }
; template <class Get, class Epi>
; DI void gemm_loop(int ntiles, int ld, char* shm, const Get& get, const Epi& epi) {
;     ...
;         if (!has_next) break;
;         G_ZERO;
;         cur = nxt; cA = nA; cB = nB; L = Ln;
;         if (wr == 1) BAR;
;     DI void operator()(const AccT& acc, int brow, int bcol, int wr, int wc, int fr, int fq) const {
;     ...
;         EPI_LOOP_ROWS { const size_t row = brow + ai * 128 + wr * 64 + m * 16 + fr; f32x4 o[2];
; #pragma unroll
;             for (int n = 0; n < 2; ++n) { const f32x4 g = acc[ai][0][m][n], u = acc[ai][1][m][n];
; #pragma unroll
;                 for (int j = 0; j < 4; ++j) o[n][j] = silu_f(g[j]) * u[j]; }
;             *(u32x4*)(ACT + row * DFF + col) = pack8(o[0], o[1]); }
	v_rcp_f32_e32 v46, v46
	v_rcp_f32_e32 v47, v47
	v_add_f32_e32 v48, 1.0, v48
	v_add_f32_e32 v49, 1.0, v49
	v_rcp_f32_e32 v48, v48
	v_rcp_f32_e32 v49, v49
	v_pk_mul_f32 v[40:41], v[40:41], v[46:47]
	v_pk_mul_f32 v[38:39], v[44:45], v[38:39]
	v_pk_mul_f32 v[40:41], v[40:41], v[32:33]
	v_pk_mul_f32 v[32:33], v[42:43], v[48:49]
	s_nop 0
	v_pk_mul_f32 v[42:43], v[32:33], v[34:35]
	v_cvt_pk_bf16_f32 v32, v36, v37
	v_mul_f32_e32 v36, 0xbfb8aa3b, v28
	v_cvt_pk_bf16_f32 v33, v38, v39
	v_exp_f32_e32 v38, v36
	v_mul_f32_e32 v36, 0xbfb8aa3b, v29
	v_exp_f32_e32 v39, v36
	v_mad_i64_i32 v[36:37], s[14:15], v50, s47, v[112:113]
	v_cvt_pk_bf16_f32 v34, v40, v41
	v_cvt_pk_bf16_f32 v35, v42, v43
	v_add_f32_e32 v38, 1.0, v38
	v_add_f32_e32 v39, 1.0, v39
	v_lshl_add_u64 v[36:37], v[36:37], 0, v[114:115]
	v_rcp_f32_e32 v38, v38
	v_rcp_f32_e32 v39, v39
	global_store_dwordx4 v[36:37], v[32:35], off sc1
	v_pk_mul_f32 v[28:29], v[28:29], v[38:39]
	s_nop 0
	v_mul_f32_e32 v32, 0xbfb8aa3b, v30
	v_mul_f32_e32 v33, 0xbfb8aa3b, v31
	v_exp_f32_e32 v32, v32
	v_exp_f32_e32 v33, v33
	v_pk_mul_f32 v[20:21], v[28:29], v[20:21]
	v_add_u32_e32 v34, 0xa0, v144
	v_add_f32_e32 v28, 1.0, v32
	v_add_f32_e32 v29, 1.0, v33
	v_mul_f32_e32 v32, 0xbfb8aa3b, v24
	v_mul_f32_e32 v33, 0xbfb8aa3b, v25
	v_rcp_f32_e32 v28, v28
	v_rcp_f32_e32 v29, v29
	v_exp_f32_e32 v32, v32
	v_exp_f32_e32 v33, v33
	v_pk_mul_f32 v[28:29], v[30:31], v[28:29]
	v_add_f32_e32 v30, 1.0, v32
	v_add_f32_e32 v31, 1.0, v33
	v_mul_f32_e32 v32, 0xbfb8aa3b, v26
	v_mul_f32_e32 v33, 0xbfb8aa3b, v27
	v_exp_f32_e32 v32, v32
	v_exp_f32_e32 v33, v33
	v_rcp_f32_e32 v30, v30
	v_rcp_f32_e32 v31, v31
	v_add_f32_e32 v32, 1.0, v32
	v_add_f32_e32 v33, 1.0, v33
	v_rcp_f32_e32 v32, v32
	v_rcp_f32_e32 v33, v33
	v_pk_mul_f32 v[24:25], v[24:25], v[30:31]
	v_pk_mul_f32 v[22:23], v[28:29], v[22:23]
	v_pk_mul_f32 v[24:25], v[24:25], v[16:17]
	v_pk_mul_f32 v[16:17], v[26:27], v[32:33]
	s_nop 0
	v_pk_mul_f32 v[26:27], v[16:17], v[18:19]
	v_cvt_pk_bf16_f32 v16, v20, v21
	v_mul_f32_e32 v20, 0xbfb8aa3b, v12
	v_cvt_pk_bf16_f32 v17, v22, v23
	v_exp_f32_e32 v22, v20
	v_mul_f32_e32 v20, 0xbfb8aa3b, v13
	v_exp_f32_e32 v23, v20
	v_mad_i64_i32 v[20:21], s[14:15], v34, s47, v[112:113]
	v_cvt_pk_bf16_f32 v18, v24, v25
	v_cvt_pk_bf16_f32 v19, v26, v27
	v_add_f32_e32 v22, 1.0, v22
	v_add_f32_e32 v23, 1.0, v23
	v_lshl_add_u64 v[20:21], v[20:21], 0, v[114:115]
	v_rcp_f32_e32 v22, v22
	v_rcp_f32_e32 v23, v23
	global_store_dwordx4 v[20:21], v[16:19], off sc1
	v_pk_mul_f32 v[12:13], v[12:13], v[22:23]
	s_nop 0
	v_mul_f32_e32 v16, 0xbfb8aa3b, v14
	v_mul_f32_e32 v17, 0xbfb8aa3b, v15
	v_exp_f32_e32 v16, v16
	v_exp_f32_e32 v17, v17
	v_pk_mul_f32 v[4:5], v[12:13], v[4:5]
	v_add_u32_e32 v18, 0xb0, v144
	v_add_f32_e32 v12, 1.0, v16
	v_add_f32_e32 v13, 1.0, v17
	v_mul_f32_e32 v16, 0xbfb8aa3b, v8
	v_mul_f32_e32 v17, 0xbfb8aa3b, v9
	v_rcp_f32_e32 v12, v12
	v_rcp_f32_e32 v13, v13
	v_exp_f32_e32 v16, v16
	v_exp_f32_e32 v17, v17
	v_pk_mul_f32 v[12:13], v[14:15], v[12:13]
	v_add_f32_e32 v14, 1.0, v16
	v_add_f32_e32 v15, 1.0, v17
	v_mul_f32_e32 v16, 0xbfb8aa3b, v10
	v_mul_f32_e32 v17, 0xbfb8aa3b, v11
	v_exp_f32_e32 v16, v16
	v_exp_f32_e32 v17, v17
	v_rcp_f32_e32 v14, v14
	v_rcp_f32_e32 v15, v15
	v_add_f32_e32 v16, 1.0, v16
	v_add_f32_e32 v17, 1.0, v17
	v_rcp_f32_e32 v16, v16
	v_rcp_f32_e32 v17, v17
	v_pk_mul_f32 v[8:9], v[8:9], v[14:15]
	v_pk_mul_f32 v[6:7], v[12:13], v[6:7]
	v_pk_mul_f32 v[8:9], v[8:9], v[0:1]
	v_pk_mul_f32 v[0:1], v[10:11], v[16:17]
	s_nop 0
	v_pk_mul_f32 v[10:11], v[0:1], v[2:3]
	v_cvt_pk_bf16_f32 v0, v4, v5
	v_mad_i64_i32 v[4:5], s[14:15], v18, s47, v[112:113]
	v_cvt_pk_bf16_f32 v1, v6, v7
	v_cvt_pk_bf16_f32 v2, v8, v9
	v_cvt_pk_bf16_f32 v3, v10, v11
	v_lshl_add_u64 v[4:5], v[4:5], 0, v[114:115]
	global_store_dwordx4 v[4:5], v[0:3], off sc1
	s_cbranch_vccnz .LBB0_759
	s_andn2_b64 vcc, exec, s[0:1]
	s_cbranch_vccnz .LBB0_758
	s_barrier
	s_branch .LBB0_758

; #define EPI_LOOP_ROWS _Pragma("unroll") for (int ai = 0; ai < 2; ++ai) _Pragma("unroll") for (int m = 0; m < 4; ++m)
; DI u32x4 pack8(const f32x4 a, const f32x4 b) { return (u32x4){pack2(a[0], a[1]), pack2(a[2], a[3]), pack2(b[0], b[1]), pack2(b[2], b[3])}; }
; DI float silu_f(float x) { return x * __builtin_amdgcn_rcpf(1.f + __expf(-x)); }
;     DI void operator()(const AccT& acc, int brow, int bcol, int wr, int wc, int fr, int fq) const {
;         const int col = (bcol >> 1) + wc * 32 + fq * 8;
;         EPI_LOOP_ROWS { const size_t row = brow + ai * 128 + wr * 64 + m * 16 + fr; f32x4 o[2];
; #pragma unroll
;             for (int n = 0; n < 2; ++n) { const f32x4 g = acc[ai][0][m][n], u = acc[ai][1][m][n];
; #pragma unroll
;                 for (int j = 0; j < 4; ++j) o[n][j] = silu_f(g[j]) * u[j]; }
;             *(u32x4*)(ACT + row * DFF + col) = pack8(o[0], o[1]); }
;     }
.LBB0_1697:
	v_mov_b32_e32 v144, v252
	s_ashr_i32 s9, s36, 1
	v_lshrrev_b32_e32 v146, 1, v144
	v_and_b32_e32 v147, 0x60, v146
	v_and_b32_e32 v146, 24, v146
	v_add3_u32 v146, v147, s9, v146
	v_mul_f32_e32 v147, 0xbfb8aa3b, v124
	v_exp_f32_e32 v147, v147
	v_mul_f32_e32 v148, 0xbfb8aa3b, v125
	v_exp_f32_e32 v149, v148
	v_and_b32_e32 v145, 15, v144
	v_add_f32_e32 v147, 1.0, v147
	v_rcp_f32_e32 v148, v147
	v_add_f32_e32 v147, 1.0, v149
	v_rcp_f32_e32 v149, v147
	v_ashrrev_i32_e32 v144, 2, v144
	v_and_b32_e32 v144, 0xffffffc0, v144
	v_add3_u32 v144, v145, s34, v144
	v_pk_mul_f32 v[124:125], v[124:125], v[148:149]
	v_mul_f32_e32 v145, 0xbfb8aa3b, v126
	v_mul_f32_e32 v148, 0xbfb8aa3b, v127
	v_exp_f32_e32 v145, v145
	v_exp_f32_e32 v148, v148
	v_pk_mul_f32 v[116:117], v[124:125], v[116:117]
	v_ashrrev_i32_e32 v147, 31, v146
	v_add_f32_e32 v124, 1.0, v145
	v_add_f32_e32 v125, 1.0, v148
	v_mul_f32_e32 v145, 0xbfb8aa3b, v120
	v_rcp_f32_e32 v124, v124
	v_rcp_f32_e32 v125, v125
	v_exp_f32_e32 v145, v145
	v_mul_f32_e32 v148, 0xbfb8aa3b, v121
	v_exp_f32_e32 v148, v148
	v_pk_mul_f32 v[124:125], v[126:127], v[124:125]
	v_add_f32_e32 v126, 1.0, v145
	v_mul_f32_e32 v145, 0xbfb8aa3b, v122
	v_add_f32_e32 v127, 1.0, v148
	v_exp_f32_e32 v145, v145
	v_mul_f32_e32 v148, 0xbfb8aa3b, v123
	v_exp_f32_e32 v149, v148
	v_rcp_f32_e32 v126, v126
	v_add_f32_e32 v145, 1.0, v145
	v_rcp_f32_e32 v127, v127
	v_rcp_f32_e32 v148, v145
	v_add_f32_e32 v145, 1.0, v149
	v_rcp_f32_e32 v149, v145
	v_pk_mul_f32 v[120:121], v[120:121], v[126:127]
	v_pk_mul_f32 v[118:119], v[124:125], v[118:119]
	v_pk_mul_f32 v[112:113], v[120:121], v[112:113]
	v_pk_mul_f32 v[120:121], v[122:123], v[148:149]
	v_cvt_pk_bf16_f32 v116, v116, v117
	v_pk_mul_f32 v[114:115], v[120:121], v[114:115]
	v_cvt_pk_bf16_f32 v117, v118, v119
	v_cvt_pk_bf16_f32 v119, v114, v115
	v_mul_f32_e32 v114, 0xbfb8aa3b, v108
	v_exp_f32_e32 v122, v114
	v_mul_f32_e32 v114, 0xbfb8aa3b, v109
	v_exp_f32_e32 v123, v114
	v_cvt_pk_bf16_f32 v118, v112, v113
	v_mov_b64_e32 v[112:113], s[96:97]
	v_mad_i64_i32 v[120:121], s[14:15], v144, s50, v[112:113]
	v_lshlrev_b64 v[114:115], 1, v[146:147]
	v_add_f32_e32 v122, 1.0, v122
	v_add_f32_e32 v123, 1.0, v123
	v_lshl_add_u64 v[120:121], v[120:121], 0, v[114:115]
	v_rcp_f32_e32 v122, v122
	v_rcp_f32_e32 v123, v123
	global_store_dwordx4 v[120:121], v[116:119], off sc1
	s_andn2_b64 vcc, exec, s[6:7]
	s_mov_b64 s[6:7], -1
	v_mul_f32_e32 v116, 0xbfb8aa3b, v110
	v_mul_f32_e32 v117, 0xbfb8aa3b, v111
	v_exp_f32_e32 v116, v116
	v_exp_f32_e32 v117, v117
	v_pk_mul_f32 v[108:109], v[108:109], v[122:123]
	v_add_u32_e32 v118, 16, v144
	v_pk_mul_f32 v[100:101], v[108:109], v[100:101]
	v_add_f32_e32 v108, 1.0, v116
	v_add_f32_e32 v109, 1.0, v117
	v_mul_f32_e32 v116, 0xbfb8aa3b, v104
	v_mul_f32_e32 v117, 0xbfb8aa3b, v105
	v_rcp_f32_e32 v108, v108
	v_rcp_f32_e32 v109, v109
	v_exp_f32_e32 v116, v116
	v_exp_f32_e32 v117, v117
	v_pk_mul_f32 v[108:109], v[110:111], v[108:109]
	v_add_f32_e32 v110, 1.0, v116
	v_add_f32_e32 v111, 1.0, v117
	v_mul_f32_e32 v116, 0xbfb8aa3b, v106
	v_mul_f32_e32 v117, 0xbfb8aa3b, v107
	v_exp_f32_e32 v116, v116
	v_exp_f32_e32 v117, v117
	v_rcp_f32_e32 v110, v110
	v_rcp_f32_e32 v111, v111
	v_add_f32_e32 v116, 1.0, v116
	v_add_f32_e32 v117, 1.0, v117
	v_rcp_f32_e32 v116, v116
	v_rcp_f32_e32 v117, v117
	v_pk_mul_f32 v[104:105], v[104:105], v[110:111]
	v_pk_mul_f32 v[102:103], v[108:109], v[102:103]
	v_pk_mul_f32 v[104:105], v[104:105], v[96:97]
	v_pk_mul_f32 v[96:97], v[106:107], v[116:117]
	s_nop 0
	v_pk_mul_f32 v[106:107], v[96:97], v[98:99]
	v_cvt_pk_bf16_f32 v96, v100, v101
	v_mul_f32_e32 v100, 0xbfb8aa3b, v92
	v_cvt_pk_bf16_f32 v97, v102, v103
	v_exp_f32_e32 v102, v100
	v_mul_f32_e32 v100, 0xbfb8aa3b, v93
	v_exp_f32_e32 v103, v100
	v_mad_i64_i32 v[100:101], s[14:15], v118, s50, v[112:113]
	v_cvt_pk_bf16_f32 v98, v104, v105
	v_cvt_pk_bf16_f32 v99, v106, v107
	v_add_f32_e32 v102, 1.0, v102
	v_add_f32_e32 v103, 1.0, v103
	v_lshl_add_u64 v[100:101], v[100:101], 0, v[114:115]
	v_rcp_f32_e32 v102, v102
	v_rcp_f32_e32 v103, v103
	global_store_dwordx4 v[100:101], v[96:99], off sc1
	v_pk_mul_f32 v[92:93], v[92:93], v[102:103]
	s_nop 0
	v_mul_f32_e32 v96, 0xbfb8aa3b, v94
	v_mul_f32_e32 v97, 0xbfb8aa3b, v95
	v_exp_f32_e32 v96, v96
	v_exp_f32_e32 v97, v97
	v_pk_mul_f32 v[84:85], v[92:93], v[84:85]
	v_add_u32_e32 v98, 32, v144
	v_add_f32_e32 v92, 1.0, v96
	v_add_f32_e32 v93, 1.0, v97
	v_mul_f32_e32 v96, 0xbfb8aa3b, v88
	v_mul_f32_e32 v97, 0xbfb8aa3b, v89
	v_rcp_f32_e32 v92, v92
	v_rcp_f32_e32 v93, v93
	v_exp_f32_e32 v96, v96
	v_exp_f32_e32 v97, v97
	v_pk_mul_f32 v[92:93], v[94:95], v[92:93]
	v_add_f32_e32 v94, 1.0, v96
	v_add_f32_e32 v95, 1.0, v97
	v_mul_f32_e32 v96, 0xbfb8aa3b, v90
	v_mul_f32_e32 v97, 0xbfb8aa3b, v91
	v_exp_f32_e32 v96, v96
	v_exp_f32_e32 v97, v97
	v_rcp_f32_e32 v94, v94
	v_rcp_f32_e32 v95, v95
	v_add_f32_e32 v96, 1.0, v96
	v_add_f32_e32 v97, 1.0, v97
	v_rcp_f32_e32 v96, v96
	v_rcp_f32_e32 v97, v97
	v_pk_mul_f32 v[88:89], v[88:89], v[94:95]
	v_pk_mul_f32 v[86:87], v[92:93], v[86:87]
	v_pk_mul_f32 v[88:89], v[88:89], v[80:81]
	v_pk_mul_f32 v[80:81], v[90:91], v[96:97]
	s_nop 0
	v_pk_mul_f32 v[90:91], v[80:81], v[82:83]
	v_cvt_pk_bf16_f32 v80, v84, v85
	v_mul_f32_e32 v84, 0xbfb8aa3b, v76
	v_cvt_pk_bf16_f32 v81, v86, v87
	v_exp_f32_e32 v86, v84
	v_mul_f32_e32 v84, 0xbfb8aa3b, v77
	v_exp_f32_e32 v87, v84
	v_mad_i64_i32 v[84:85], s[14:15], v98, s50, v[112:113]
	v_cvt_pk_bf16_f32 v82, v88, v89
	v_cvt_pk_bf16_f32 v83, v90, v91
	v_add_f32_e32 v86, 1.0, v86
	v_add_f32_e32 v87, 1.0, v87
	v_lshl_add_u64 v[84:85], v[84:85], 0, v[114:115]
	v_rcp_f32_e32 v86, v86
	v_rcp_f32_e32 v87, v87
; #define EPI_LOOP_ROWS _Pragma("unroll") for (int ai = 0; ai < 2; ++ai) _Pragma("unroll") for (int m = 0; m < 4; ++m)
; DI u32x4 pack8(const f32x4 a, const f32x4 b) { return (u32x4){pack2(a[0], a[1]), pack2(a[2], a[3]), pack2(b[0], b[1]), pack2(b[2], b[3])}; }
; DI float silu_f(float x) { return x * __builtin_amdgcn_rcpf(1.f + __expf(-x)); }
;     DI void operator()(const AccT& acc, int brow, int bcol, int wr, int wc, int fr, int fq) const {
;     ...
;         EPI_LOOP_ROWS { const size_t row = brow + ai * 128 + wr * 64 + m * 16 + fr; f32x4 o[2];
; #pragma unroll
;             for (int n = 0; n < 2; ++n) { const f32x4 g = acc[ai][0][m][n], u = acc[ai][1][m][n];
; #pragma unroll
;                 for (int j = 0; j < 4; ++j) o[n][j] = silu_f(g[j]) * u[j]; }
;             *(u32x4*)(ACT + row * DFF + col) = pack8(o[0], o[1]); }
	global_store_dwordx4 v[84:85], v[80:83], off sc1
	v_pk_mul_f32 v[76:77], v[76:77], v[86:87]
	s_nop 0
	v_mul_f32_e32 v80, 0xbfb8aa3b, v78
	v_mul_f32_e32 v81, 0xbfb8aa3b, v79
	v_exp_f32_e32 v80, v80
	v_exp_f32_e32 v81, v81
	v_pk_mul_f32 v[68:69], v[76:77], v[68:69]
	v_add_u32_e32 v82, 48, v144
	v_add_f32_e32 v76, 1.0, v80
	v_add_f32_e32 v77, 1.0, v81
	v_mul_f32_e32 v80, 0xbfb8aa3b, v72
	v_mul_f32_e32 v81, 0xbfb8aa3b, v73
	v_rcp_f32_e32 v76, v76
	v_rcp_f32_e32 v77, v77
	v_exp_f32_e32 v80, v80
	v_exp_f32_e32 v81, v81
	v_pk_mul_f32 v[76:77], v[78:79], v[76:77]
	v_add_f32_e32 v78, 1.0, v80
	v_add_f32_e32 v79, 1.0, v81
	v_mul_f32_e32 v80, 0xbfb8aa3b, v74
	v_mul_f32_e32 v81, 0xbfb8aa3b, v75
	v_exp_f32_e32 v80, v80
	v_exp_f32_e32 v81, v81
	v_rcp_f32_e32 v78, v78
	v_rcp_f32_e32 v79, v79
	v_add_f32_e32 v80, 1.0, v80
	v_add_f32_e32 v81, 1.0, v81
	v_rcp_f32_e32 v80, v80
	v_rcp_f32_e32 v81, v81
	v_pk_mul_f32 v[72:73], v[72:73], v[78:79]
	v_pk_mul_f32 v[70:71], v[76:77], v[70:71]
	v_pk_mul_f32 v[72:73], v[72:73], v[64:65]
	v_pk_mul_f32 v[64:65], v[74:75], v[80:81]
	s_nop 0
	v_pk_mul_f32 v[74:75], v[64:65], v[66:67]
	v_cvt_pk_bf16_f32 v64, v68, v69
	v_mul_f32_e32 v68, 0xbfb8aa3b, v60
	v_cvt_pk_bf16_f32 v65, v70, v71
	v_exp_f32_e32 v70, v68
	v_mul_f32_e32 v68, 0xbfb8aa3b, v61
	v_exp_f32_e32 v71, v68
	v_mad_i64_i32 v[68:69], s[14:15], v82, s50, v[112:113]
	v_cvt_pk_bf16_f32 v66, v72, v73
	v_cvt_pk_bf16_f32 v67, v74, v75
	v_add_f32_e32 v70, 1.0, v70
	v_add_f32_e32 v71, 1.0, v71
	v_lshl_add_u64 v[68:69], v[68:69], 0, v[114:115]
	v_rcp_f32_e32 v70, v70
	v_rcp_f32_e32 v71, v71
	global_store_dwordx4 v[68:69], v[64:67], off sc1
	v_pk_mul_f32 v[60:61], v[60:61], v[70:71]
	s_nop 0
	v_mul_f32_e32 v64, 0xbfb8aa3b, v62
	v_mul_f32_e32 v65, 0xbfb8aa3b, v63
	v_exp_f32_e32 v64, v64
	v_exp_f32_e32 v65, v65
	v_pk_mul_f32 v[52:53], v[60:61], v[52:53]
	v_add_u32_e32 v66, 0x80, v144
	v_add_f32_e32 v60, 1.0, v64
	v_add_f32_e32 v61, 1.0, v65
	v_mul_f32_e32 v64, 0xbfb8aa3b, v56
	v_mul_f32_e32 v65, 0xbfb8aa3b, v57
	v_rcp_f32_e32 v60, v60
	v_rcp_f32_e32 v61, v61
	v_exp_f32_e32 v64, v64
	v_exp_f32_e32 v65, v65
	v_pk_mul_f32 v[60:61], v[62:63], v[60:61]
	v_add_f32_e32 v62, 1.0, v64
	v_add_f32_e32 v63, 1.0, v65
	v_mul_f32_e32 v64, 0xbfb8aa3b, v58
	v_mul_f32_e32 v65, 0xbfb8aa3b, v59
	v_exp_f32_e32 v64, v64
	v_exp_f32_e32 v65, v65
	v_rcp_f32_e32 v62, v62
	v_rcp_f32_e32 v63, v63
	v_add_f32_e32 v64, 1.0, v64
	v_add_f32_e32 v65, 1.0, v65
	v_rcp_f32_e32 v64, v64
	v_rcp_f32_e32 v65, v65
	v_pk_mul_f32 v[56:57], v[56:57], v[62:63]
	v_pk_mul_f32 v[54:55], v[60:61], v[54:55]
	v_pk_mul_f32 v[56:57], v[56:57], v[48:49]
	v_pk_mul_f32 v[48:49], v[58:59], v[64:65]
	s_nop 0
	v_pk_mul_f32 v[58:59], v[48:49], v[50:51]
	v_cvt_pk_bf16_f32 v48, v52, v53
	v_mul_f32_e32 v52, 0xbfb8aa3b, v44
	v_cvt_pk_bf16_f32 v49, v54, v55
	v_exp_f32_e32 v54, v52
	v_mul_f32_e32 v52, 0xbfb8aa3b, v45
	v_exp_f32_e32 v55, v52
	v_mad_i64_i32 v[52:53], s[14:15], v66, s50, v[112:113]
	v_cvt_pk_bf16_f32 v50, v56, v57
	v_cvt_pk_bf16_f32 v51, v58, v59
	v_add_f32_e32 v54, 1.0, v54
	v_add_f32_e32 v55, 1.0, v55
	v_lshl_add_u64 v[52:53], v[52:53], 0, v[114:115]
	v_rcp_f32_e32 v54, v54
	v_rcp_f32_e32 v55, v55
	global_store_dwordx4 v[52:53], v[48:51], off sc1
	v_pk_mul_f32 v[44:45], v[44:45], v[54:55]
	s_nop 0
	v_mul_f32_e32 v48, 0xbfb8aa3b, v46
	v_mul_f32_e32 v49, 0xbfb8aa3b, v47
	v_exp_f32_e32 v48, v48
	v_exp_f32_e32 v49, v49
	v_pk_mul_f32 v[36:37], v[44:45], v[36:37]
	v_add_u32_e32 v50, 0x90, v144
	v_add_f32_e32 v44, 1.0, v48
	v_add_f32_e32 v45, 1.0, v49
	v_mul_f32_e32 v48, 0xbfb8aa3b, v40
	v_mul_f32_e32 v49, 0xbfb8aa3b, v41
	v_rcp_f32_e32 v44, v44
	v_rcp_f32_e32 v45, v45
	v_exp_f32_e32 v48, v48
	v_exp_f32_e32 v49, v49
	v_pk_mul_f32 v[44:45], v[46:47], v[44:45]
	v_add_f32_e32 v46, 1.0, v48
	v_add_f32_e32 v47, 1.0, v49
	v_mul_f32_e32 v48, 0xbfb8aa3b, v42
	v_mul_f32_e32 v49, 0xbfb8aa3b, v43
	v_exp_f32_e32 v48, v48
	v_exp_f32_e32 v49, v49
; DI float silu_f(float x) { return x * __builtin_amdgcn_rcpf(1.f + __expf(-x)); }
; #define BAR __builtin_amdgcn_s_barrier()
; #define EPI_LOOP_ROWS _Pragma("unroll") for (int ai = 0; ai < 2; ++ai) _Pragma("unroll") for (int m = 0; m < 4; ++m)
; DI u32x4 pack8(const f32x4 a, const f32x4 b) { return (u32x4){pack2(a[0], a[1]), pack2(a[2], a[3]), pack2(b[0], b[1]), pack2(b[2], b[3])}; }
; template <class Get, class Epi>
; DI void gemm_loop(int ntiles, int ld, char* shm, const Get& get, const Epi& epi) {
;     ...
;         if (!has_next) break;
;         G_ZERO;
;         cur = nxt; cA = nA; cB = nB; L = Ln;
;         if (wr == 1) BAR;
;     DI void operator()(const AccT& acc, int brow, int bcol, int wr, int wc, int fr, int fq) const {
;     ...
;         EPI_LOOP_ROWS { const size_t row = brow + ai * 128 + wr * 64 + m * 16 + fr; f32x4 o[2];
; #pragma unroll
;             for (int n = 0; n < 2; ++n) { const f32x4 g = acc[ai][0][m][n], u = acc[ai][1][m][n];
; #pragma unroll
;                 for (int j = 0; j < 4; ++j) o[n][j] = silu_f(g[j]) * u[j]; }
;             *(u32x4*)(ACT + row * DFF + col) = pack8(o[0], o[1]); }
	v_rcp_f32_e32 v46, v46
	v_rcp_f32_e32 v47, v47
	v_add_f32_e32 v48, 1.0, v48
	v_add_f32_e32 v49, 1.0, v49
	v_rcp_f32_e32 v48, v48
	v_rcp_f32_e32 v49, v49
	v_pk_mul_f32 v[40:41], v[40:41], v[46:47]
	v_pk_mul_f32 v[38:39], v[44:45], v[38:39]
	v_pk_mul_f32 v[40:41], v[40:41], v[32:33]
	v_pk_mul_f32 v[32:33], v[42:43], v[48:49]
	s_nop 0
	v_pk_mul_f32 v[42:43], v[32:33], v[34:35]
	v_cvt_pk_bf16_f32 v32, v36, v37
	v_mul_f32_e32 v36, 0xbfb8aa3b, v28
	v_cvt_pk_bf16_f32 v33, v38, v39
	v_exp_f32_e32 v38, v36
	v_mul_f32_e32 v36, 0xbfb8aa3b, v29
	v_exp_f32_e32 v39, v36
	v_mad_i64_i32 v[36:37], s[14:15], v50, s50, v[112:113]
	v_cvt_pk_bf16_f32 v34, v40, v41
	v_cvt_pk_bf16_f32 v35, v42, v43
	v_add_f32_e32 v38, 1.0, v38
	v_add_f32_e32 v39, 1.0, v39
	v_lshl_add_u64 v[36:37], v[36:37], 0, v[114:115]
	v_rcp_f32_e32 v38, v38
	v_rcp_f32_e32 v39, v39
	global_store_dwordx4 v[36:37], v[32:35], off sc1
	v_pk_mul_f32 v[28:29], v[28:29], v[38:39]
	s_nop 0
	v_mul_f32_e32 v32, 0xbfb8aa3b, v30
	v_mul_f32_e32 v33, 0xbfb8aa3b, v31
	v_exp_f32_e32 v32, v32
	v_exp_f32_e32 v33, v33
	v_pk_mul_f32 v[20:21], v[28:29], v[20:21]
	v_add_u32_e32 v34, 0xa0, v144
	v_add_f32_e32 v28, 1.0, v32
	v_add_f32_e32 v29, 1.0, v33
	v_mul_f32_e32 v32, 0xbfb8aa3b, v24
	v_mul_f32_e32 v33, 0xbfb8aa3b, v25
	v_rcp_f32_e32 v28, v28
	v_rcp_f32_e32 v29, v29
	v_exp_f32_e32 v32, v32
	v_exp_f32_e32 v33, v33
	v_pk_mul_f32 v[28:29], v[30:31], v[28:29]
	v_add_f32_e32 v30, 1.0, v32
	v_add_f32_e32 v31, 1.0, v33
	v_mul_f32_e32 v32, 0xbfb8aa3b, v26
	v_mul_f32_e32 v33, 0xbfb8aa3b, v27
	v_exp_f32_e32 v32, v32
	v_exp_f32_e32 v33, v33
	v_rcp_f32_e32 v30, v30
	v_rcp_f32_e32 v31, v31
	v_add_f32_e32 v32, 1.0, v32
	v_add_f32_e32 v33, 1.0, v33
	v_rcp_f32_e32 v32, v32
	v_rcp_f32_e32 v33, v33
	v_pk_mul_f32 v[24:25], v[24:25], v[30:31]
	v_pk_mul_f32 v[22:23], v[28:29], v[22:23]
	v_pk_mul_f32 v[24:25], v[24:25], v[16:17]
	v_pk_mul_f32 v[16:17], v[26:27], v[32:33]
	s_nop 0
	v_pk_mul_f32 v[26:27], v[16:17], v[18:19]
	v_cvt_pk_bf16_f32 v16, v20, v21
	v_mul_f32_e32 v20, 0xbfb8aa3b, v12
	v_cvt_pk_bf16_f32 v17, v22, v23
	v_exp_f32_e32 v22, v20
	v_mul_f32_e32 v20, 0xbfb8aa3b, v13
	v_exp_f32_e32 v23, v20
	v_mad_i64_i32 v[20:21], s[14:15], v34, s50, v[112:113]
	v_cvt_pk_bf16_f32 v18, v24, v25
	v_cvt_pk_bf16_f32 v19, v26, v27
	v_add_f32_e32 v22, 1.0, v22
	v_add_f32_e32 v23, 1.0, v23
	v_lshl_add_u64 v[20:21], v[20:21], 0, v[114:115]
	v_rcp_f32_e32 v22, v22
	v_rcp_f32_e32 v23, v23
	global_store_dwordx4 v[20:21], v[16:19], off sc1
	v_pk_mul_f32 v[12:13], v[12:13], v[22:23]
	s_nop 0
	v_mul_f32_e32 v16, 0xbfb8aa3b, v14
	v_mul_f32_e32 v17, 0xbfb8aa3b, v15
	v_exp_f32_e32 v16, v16
	v_exp_f32_e32 v17, v17
	v_pk_mul_f32 v[4:5], v[12:13], v[4:5]
	v_add_u32_e32 v18, 0xb0, v144
	v_add_f32_e32 v12, 1.0, v16
	v_add_f32_e32 v13, 1.0, v17
	v_mul_f32_e32 v16, 0xbfb8aa3b, v8
	v_mul_f32_e32 v17, 0xbfb8aa3b, v9
	v_rcp_f32_e32 v12, v12
	v_rcp_f32_e32 v13, v13
	v_exp_f32_e32 v16, v16
	v_exp_f32_e32 v17, v17
	v_pk_mul_f32 v[12:13], v[14:15], v[12:13]
	v_add_f32_e32 v14, 1.0, v16
	v_add_f32_e32 v15, 1.0, v17
	v_mul_f32_e32 v16, 0xbfb8aa3b, v10
	v_mul_f32_e32 v17, 0xbfb8aa3b, v11
	v_exp_f32_e32 v16, v16
	v_exp_f32_e32 v17, v17
	v_rcp_f32_e32 v14, v14
	v_rcp_f32_e32 v15, v15
	v_add_f32_e32 v16, 1.0, v16
	v_add_f32_e32 v17, 1.0, v17
	v_rcp_f32_e32 v16, v16
	v_rcp_f32_e32 v17, v17
	v_pk_mul_f32 v[8:9], v[8:9], v[14:15]
	v_pk_mul_f32 v[6:7], v[12:13], v[6:7]
	v_pk_mul_f32 v[8:9], v[8:9], v[0:1]
	v_pk_mul_f32 v[0:1], v[10:11], v[16:17]
	s_nop 0
	v_pk_mul_f32 v[10:11], v[0:1], v[2:3]
	v_cvt_pk_bf16_f32 v0, v4, v5
	v_mad_i64_i32 v[4:5], s[14:15], v18, s50, v[112:113]
	v_cvt_pk_bf16_f32 v1, v6, v7
	v_cvt_pk_bf16_f32 v2, v8, v9
	v_cvt_pk_bf16_f32 v3, v10, v11
	v_lshl_add_u64 v[4:5], v[4:5], 0, v[114:115]
	global_store_dwordx4 v[4:5], v[0:3], off sc1
	s_cbranch_vccnz .LBB0_1690
	s_andn2_b64 vcc, exec, s[0:1]
	s_cbranch_vccnz .LBB0_1689
	s_barrier
	s_branch .LBB0_1689

; #define EPI_LOOP_ROWS _Pragma("unroll") for (int ai = 0; ai < 2; ++ai) _Pragma("unroll") for (int m = 0; m < 4; ++m)
; DI u32x4 pack8(const f32x4 a, const f32x4 b) { return (u32x4){pack2(a[0], a[1]), pack2(a[2], a[3]), pack2(b[0], b[1]), pack2(b[2], b[3])}; }
; DI float silu_f(float x) { return x * __builtin_amdgcn_rcpf(1.f + __expf(-x)); }
;     DI void operator()(const AccT& acc, int brow, int bcol, int wr, int wc, int fr, int fq) const {
;         const int col = (bcol >> 1) + wc * 32 + fq * 8;
;         EPI_LOOP_ROWS { const size_t row = brow + ai * 128 + wr * 64 + m * 16 + fr; f32x4 o[2];
; #pragma unroll
;             for (int n = 0; n < 2; ++n) { const f32x4 g = acc[ai][0][m][n], u = acc[ai][1][m][n];
; #pragma unroll
;                 for (int j = 0; j < 4; ++j) o[n][j] = silu_f(g[j]) * u[j]; }
;             *(u32x4*)(ACT + row * DFF + col) = pack8(o[0], o[1]); }
;     }
.LBB0_3682:
	v_mov_b32_e32 v144, v252
	s_ashr_i32 s9, s30, 1
	v_lshrrev_b32_e32 v146, 1, v144
	v_and_b32_e32 v147, 0x60, v146
	v_and_b32_e32 v146, 24, v146
	v_add3_u32 v146, v147, s9, v146
	v_mul_f32_e32 v147, 0xbfb8aa3b, v124
	v_exp_f32_e32 v147, v147
	v_mul_f32_e32 v148, 0xbfb8aa3b, v125
	v_exp_f32_e32 v149, v148
	v_and_b32_e32 v145, 15, v144
	v_add_f32_e32 v147, 1.0, v147
	v_rcp_f32_e32 v148, v147
	v_add_f32_e32 v147, 1.0, v149
	v_rcp_f32_e32 v149, v147
	v_ashrrev_i32_e32 v144, 2, v144
	v_and_b32_e32 v144, 0xffffffc0, v144
	v_add3_u32 v144, v145, s24, v144
	v_pk_mul_f32 v[124:125], v[124:125], v[148:149]
	v_mul_f32_e32 v145, 0xbfb8aa3b, v126
	v_mul_f32_e32 v148, 0xbfb8aa3b, v127
	v_exp_f32_e32 v145, v145
	v_exp_f32_e32 v148, v148
	v_pk_mul_f32 v[116:117], v[124:125], v[116:117]
	v_ashrrev_i32_e32 v147, 31, v146
	v_add_f32_e32 v124, 1.0, v145
	v_add_f32_e32 v125, 1.0, v148
	v_mul_f32_e32 v145, 0xbfb8aa3b, v120
	v_rcp_f32_e32 v124, v124
	v_rcp_f32_e32 v125, v125
	v_exp_f32_e32 v145, v145
	v_mul_f32_e32 v148, 0xbfb8aa3b, v121
	v_exp_f32_e32 v148, v148
	v_pk_mul_f32 v[124:125], v[126:127], v[124:125]
	v_add_f32_e32 v126, 1.0, v145
	v_mul_f32_e32 v145, 0xbfb8aa3b, v122
	v_add_f32_e32 v127, 1.0, v148
	v_exp_f32_e32 v145, v145
	v_mul_f32_e32 v148, 0xbfb8aa3b, v123
	v_exp_f32_e32 v149, v148
	v_rcp_f32_e32 v126, v126
	v_add_f32_e32 v145, 1.0, v145
	v_rcp_f32_e32 v127, v127
	v_rcp_f32_e32 v148, v145
	v_add_f32_e32 v145, 1.0, v149
	v_rcp_f32_e32 v149, v145
	v_pk_mul_f32 v[120:121], v[120:121], v[126:127]
	v_pk_mul_f32 v[118:119], v[124:125], v[118:119]
	v_pk_mul_f32 v[112:113], v[120:121], v[112:113]
	v_pk_mul_f32 v[120:121], v[122:123], v[148:149]
	v_cvt_pk_bf16_f32 v116, v116, v117
	v_pk_mul_f32 v[114:115], v[120:121], v[114:115]
	v_cvt_pk_bf16_f32 v117, v118, v119
	v_cvt_pk_bf16_f32 v119, v114, v115
	v_mul_f32_e32 v114, 0xbfb8aa3b, v108
	v_exp_f32_e32 v122, v114
	v_mul_f32_e32 v114, 0xbfb8aa3b, v109
	v_exp_f32_e32 v123, v114
	v_cvt_pk_bf16_f32 v118, v112, v113
	v_mov_b64_e32 v[112:113], s[96:97]
	v_mad_i64_i32 v[120:121], s[14:15], v144, s46, v[112:113]
	v_lshlrev_b64 v[114:115], 1, v[146:147]
	v_add_f32_e32 v122, 1.0, v122
	v_add_f32_e32 v123, 1.0, v123
	v_lshl_add_u64 v[120:121], v[120:121], 0, v[114:115]
	v_rcp_f32_e32 v122, v122
	v_rcp_f32_e32 v123, v123
	global_store_dwordx4 v[120:121], v[116:119], off sc1
	s_andn2_b64 vcc, exec, s[6:7]
	s_mov_b64 s[6:7], -1
	v_mul_f32_e32 v116, 0xbfb8aa3b, v110
	v_mul_f32_e32 v117, 0xbfb8aa3b, v111
	v_exp_f32_e32 v116, v116
	v_exp_f32_e32 v117, v117
	v_pk_mul_f32 v[108:109], v[108:109], v[122:123]
	v_add_u32_e32 v118, 16, v144
	v_pk_mul_f32 v[100:101], v[108:109], v[100:101]
	v_add_f32_e32 v108, 1.0, v116
	v_add_f32_e32 v109, 1.0, v117
	v_mul_f32_e32 v116, 0xbfb8aa3b, v104
	v_mul_f32_e32 v117, 0xbfb8aa3b, v105
	v_rcp_f32_e32 v108, v108
	v_rcp_f32_e32 v109, v109
	v_exp_f32_e32 v116, v116
	v_exp_f32_e32 v117, v117
	v_pk_mul_f32 v[108:109], v[110:111], v[108:109]
	v_add_f32_e32 v110, 1.0, v116
	v_add_f32_e32 v111, 1.0, v117
	v_mul_f32_e32 v116, 0xbfb8aa3b, v106
	v_mul_f32_e32 v117, 0xbfb8aa3b, v107
	v_exp_f32_e32 v116, v116
	v_exp_f32_e32 v117, v117
	v_rcp_f32_e32 v110, v110
	v_rcp_f32_e32 v111, v111
	v_add_f32_e32 v116, 1.0, v116
	v_add_f32_e32 v117, 1.0, v117
	v_rcp_f32_e32 v116, v116
	v_rcp_f32_e32 v117, v117
	v_pk_mul_f32 v[104:105], v[104:105], v[110:111]
	v_pk_mul_f32 v[102:103], v[108:109], v[102:103]
	v_pk_mul_f32 v[104:105], v[104:105], v[96:97]
	v_pk_mul_f32 v[96:97], v[106:107], v[116:117]
	s_nop 0
	v_pk_mul_f32 v[106:107], v[96:97], v[98:99]
	v_cvt_pk_bf16_f32 v96, v100, v101
	v_mul_f32_e32 v100, 0xbfb8aa3b, v92
	v_cvt_pk_bf16_f32 v97, v102, v103
	v_exp_f32_e32 v102, v100
	v_mul_f32_e32 v100, 0xbfb8aa3b, v93
	v_exp_f32_e32 v103, v100
	v_mad_i64_i32 v[100:101], s[14:15], v118, s46, v[112:113]
	v_cvt_pk_bf16_f32 v98, v104, v105
	v_cvt_pk_bf16_f32 v99, v106, v107
	v_add_f32_e32 v102, 1.0, v102
	v_add_f32_e32 v103, 1.0, v103
	v_lshl_add_u64 v[100:101], v[100:101], 0, v[114:115]
	v_rcp_f32_e32 v102, v102
	v_rcp_f32_e32 v103, v103
	global_store_dwordx4 v[100:101], v[96:99], off sc1
	v_pk_mul_f32 v[92:93], v[92:93], v[102:103]
	s_nop 0
	v_mul_f32_e32 v96, 0xbfb8aa3b, v94
	v_mul_f32_e32 v97, 0xbfb8aa3b, v95
	v_exp_f32_e32 v96, v96
	v_exp_f32_e32 v97, v97
	v_pk_mul_f32 v[84:85], v[92:93], v[84:85]
	v_add_u32_e32 v98, 32, v144
	v_add_f32_e32 v92, 1.0, v96
	v_add_f32_e32 v93, 1.0, v97
	v_mul_f32_e32 v96, 0xbfb8aa3b, v88
	v_mul_f32_e32 v97, 0xbfb8aa3b, v89
	v_rcp_f32_e32 v92, v92
	v_rcp_f32_e32 v93, v93
	v_exp_f32_e32 v96, v96
	v_exp_f32_e32 v97, v97
	v_pk_mul_f32 v[92:93], v[94:95], v[92:93]
	v_add_f32_e32 v94, 1.0, v96
	v_add_f32_e32 v95, 1.0, v97
	v_mul_f32_e32 v96, 0xbfb8aa3b, v90
	v_mul_f32_e32 v97, 0xbfb8aa3b, v91
	v_exp_f32_e32 v96, v96
	v_exp_f32_e32 v97, v97
	v_rcp_f32_e32 v94, v94
	v_rcp_f32_e32 v95, v95
	v_add_f32_e32 v96, 1.0, v96
	v_add_f32_e32 v97, 1.0, v97
	v_rcp_f32_e32 v96, v96
	v_rcp_f32_e32 v97, v97
	v_pk_mul_f32 v[88:89], v[88:89], v[94:95]
	v_pk_mul_f32 v[86:87], v[92:93], v[86:87]
	v_pk_mul_f32 v[88:89], v[88:89], v[80:81]
	v_pk_mul_f32 v[80:81], v[90:91], v[96:97]
	s_nop 0
	v_pk_mul_f32 v[90:91], v[80:81], v[82:83]
	v_cvt_pk_bf16_f32 v80, v84, v85
	v_mul_f32_e32 v84, 0xbfb8aa3b, v76
	v_cvt_pk_bf16_f32 v81, v86, v87
	v_exp_f32_e32 v86, v84
	v_mul_f32_e32 v84, 0xbfb8aa3b, v77
	v_exp_f32_e32 v87, v84
	v_mad_i64_i32 v[84:85], s[14:15], v98, s46, v[112:113]
	v_cvt_pk_bf16_f32 v82, v88, v89
	v_cvt_pk_bf16_f32 v83, v90, v91
	v_add_f32_e32 v86, 1.0, v86
	v_add_f32_e32 v87, 1.0, v87
	v_lshl_add_u64 v[84:85], v[84:85], 0, v[114:115]
	v_rcp_f32_e32 v86, v86
	v_rcp_f32_e32 v87, v87
; #define EPI_LOOP_ROWS _Pragma("unroll") for (int ai = 0; ai < 2; ++ai) _Pragma("unroll") for (int m = 0; m < 4; ++m)
; DI u32x4 pack8(const f32x4 a, const f32x4 b) { return (u32x4){pack2(a[0], a[1]), pack2(a[2], a[3]), pack2(b[0], b[1]), pack2(b[2], b[3])}; }
; DI float silu_f(float x) { return x * __builtin_amdgcn_rcpf(1.f + __expf(-x)); }
;     DI void operator()(const AccT& acc, int brow, int bcol, int wr, int wc, int fr, int fq) const {
;     ...
;         EPI_LOOP_ROWS { const size_t row = brow + ai * 128 + wr * 64 + m * 16 + fr; f32x4 o[2];
; #pragma unroll
;             for (int n = 0; n < 2; ++n) { const f32x4 g = acc[ai][0][m][n], u = acc[ai][1][m][n];
; #pragma unroll
;                 for (int j = 0; j < 4; ++j) o[n][j] = silu_f(g[j]) * u[j]; }
;             *(u32x4*)(ACT + row * DFF + col) = pack8(o[0], o[1]); }
	global_store_dwordx4 v[84:85], v[80:83], off sc1
	v_pk_mul_f32 v[76:77], v[76:77], v[86:87]
	s_nop 0
	v_mul_f32_e32 v80, 0xbfb8aa3b, v78
	v_mul_f32_e32 v81, 0xbfb8aa3b, v79
	v_exp_f32_e32 v80, v80
	v_exp_f32_e32 v81, v81
	v_pk_mul_f32 v[68:69], v[76:77], v[68:69]
	v_add_u32_e32 v82, 48, v144
	v_add_f32_e32 v76, 1.0, v80
	v_add_f32_e32 v77, 1.0, v81
	v_mul_f32_e32 v80, 0xbfb8aa3b, v72
	v_mul_f32_e32 v81, 0xbfb8aa3b, v73
	v_rcp_f32_e32 v76, v76
	v_rcp_f32_e32 v77, v77
	v_exp_f32_e32 v80, v80
	v_exp_f32_e32 v81, v81
	v_pk_mul_f32 v[76:77], v[78:79], v[76:77]
	v_add_f32_e32 v78, 1.0, v80
	v_add_f32_e32 v79, 1.0, v81
	v_mul_f32_e32 v80, 0xbfb8aa3b, v74
	v_mul_f32_e32 v81, 0xbfb8aa3b, v75
	v_exp_f32_e32 v80, v80
	v_exp_f32_e32 v81, v81
	v_rcp_f32_e32 v78, v78
	v_rcp_f32_e32 v79, v79
	v_add_f32_e32 v80, 1.0, v80
	v_add_f32_e32 v81, 1.0, v81
	v_rcp_f32_e32 v80, v80
	v_rcp_f32_e32 v81, v81
	v_pk_mul_f32 v[72:73], v[72:73], v[78:79]
	v_pk_mul_f32 v[70:71], v[76:77], v[70:71]
	v_pk_mul_f32 v[72:73], v[72:73], v[64:65]
	v_pk_mul_f32 v[64:65], v[74:75], v[80:81]
	s_nop 0
	v_pk_mul_f32 v[74:75], v[64:65], v[66:67]
	v_cvt_pk_bf16_f32 v64, v68, v69
	v_mul_f32_e32 v68, 0xbfb8aa3b, v60
	v_cvt_pk_bf16_f32 v65, v70, v71
	v_exp_f32_e32 v70, v68
	v_mul_f32_e32 v68, 0xbfb8aa3b, v61
	v_exp_f32_e32 v71, v68
	v_mad_i64_i32 v[68:69], s[14:15], v82, s46, v[112:113]
	v_cvt_pk_bf16_f32 v66, v72, v73
	v_cvt_pk_bf16_f32 v67, v74, v75
	v_add_f32_e32 v70, 1.0, v70
	v_add_f32_e32 v71, 1.0, v71
	v_lshl_add_u64 v[68:69], v[68:69], 0, v[114:115]
	v_rcp_f32_e32 v70, v70
	v_rcp_f32_e32 v71, v71
	global_store_dwordx4 v[68:69], v[64:67], off sc1
	v_pk_mul_f32 v[60:61], v[60:61], v[70:71]
	s_nop 0
	v_mul_f32_e32 v64, 0xbfb8aa3b, v62
	v_mul_f32_e32 v65, 0xbfb8aa3b, v63
	v_exp_f32_e32 v64, v64
	v_exp_f32_e32 v65, v65
	v_pk_mul_f32 v[52:53], v[60:61], v[52:53]
	v_add_u32_e32 v66, 0x80, v144
	v_add_f32_e32 v60, 1.0, v64
	v_add_f32_e32 v61, 1.0, v65
	v_mul_f32_e32 v64, 0xbfb8aa3b, v56
	v_mul_f32_e32 v65, 0xbfb8aa3b, v57
	v_rcp_f32_e32 v60, v60
	v_rcp_f32_e32 v61, v61
	v_exp_f32_e32 v64, v64
	v_exp_f32_e32 v65, v65
	v_pk_mul_f32 v[60:61], v[62:63], v[60:61]
	v_add_f32_e32 v62, 1.0, v64
	v_add_f32_e32 v63, 1.0, v65
	v_mul_f32_e32 v64, 0xbfb8aa3b, v58
	v_mul_f32_e32 v65, 0xbfb8aa3b, v59
	v_exp_f32_e32 v64, v64
	v_exp_f32_e32 v65, v65
	v_rcp_f32_e32 v62, v62
	v_rcp_f32_e32 v63, v63
	v_add_f32_e32 v64, 1.0, v64
	v_add_f32_e32 v65, 1.0, v65
	v_rcp_f32_e32 v64, v64
	v_rcp_f32_e32 v65, v65
	v_pk_mul_f32 v[56:57], v[56:57], v[62:63]
	v_pk_mul_f32 v[54:55], v[60:61], v[54:55]
	v_pk_mul_f32 v[56:57], v[56:57], v[48:49]
	v_pk_mul_f32 v[48:49], v[58:59], v[64:65]
	s_nop 0
	v_pk_mul_f32 v[58:59], v[48:49], v[50:51]
	v_cvt_pk_bf16_f32 v48, v52, v53
	v_mul_f32_e32 v52, 0xbfb8aa3b, v44
	v_cvt_pk_bf16_f32 v49, v54, v55
	v_exp_f32_e32 v54, v52
	v_mul_f32_e32 v52, 0xbfb8aa3b, v45
	v_exp_f32_e32 v55, v52
	v_mad_i64_i32 v[52:53], s[14:15], v66, s46, v[112:113]
	v_cvt_pk_bf16_f32 v50, v56, v57
	v_cvt_pk_bf16_f32 v51, v58, v59
	v_add_f32_e32 v54, 1.0, v54
	v_add_f32_e32 v55, 1.0, v55
	v_lshl_add_u64 v[52:53], v[52:53], 0, v[114:115]
	v_rcp_f32_e32 v54, v54
	v_rcp_f32_e32 v55, v55
	global_store_dwordx4 v[52:53], v[48:51], off sc1
	v_pk_mul_f32 v[44:45], v[44:45], v[54:55]
	s_nop 0
	v_mul_f32_e32 v48, 0xbfb8aa3b, v46
	v_mul_f32_e32 v49, 0xbfb8aa3b, v47
	v_exp_f32_e32 v48, v48
	v_exp_f32_e32 v49, v49
	v_pk_mul_f32 v[36:37], v[44:45], v[36:37]
	v_add_u32_e32 v50, 0x90, v144
	v_add_f32_e32 v44, 1.0, v48
	v_add_f32_e32 v45, 1.0, v49
	v_mul_f32_e32 v48, 0xbfb8aa3b, v40
	v_mul_f32_e32 v49, 0xbfb8aa3b, v41
	v_rcp_f32_e32 v44, v44
	v_rcp_f32_e32 v45, v45
	v_exp_f32_e32 v48, v48
	v_exp_f32_e32 v49, v49
	v_pk_mul_f32 v[44:45], v[46:47], v[44:45]
	v_add_f32_e32 v46, 1.0, v48
	v_add_f32_e32 v47, 1.0, v49
	v_mul_f32_e32 v48, 0xbfb8aa3b, v42
	v_mul_f32_e32 v49, 0xbfb8aa3b, v43
	v_exp_f32_e32 v48, v48
	v_exp_f32_e32 v49, v49
; DI float silu_f(float x) { return x * __builtin_amdgcn_rcpf(1.f + __expf(-x)); }
; #define BAR __builtin_amdgcn_s_barrier()
; #define EPI_LOOP_ROWS _Pragma("unroll") for (int ai = 0; ai < 2; ++ai) _Pragma("unroll") for (int m = 0; m < 4; ++m)
; DI u32x4 pack8(const f32x4 a, const f32x4 b) { return (u32x4){pack2(a[0], a[1]), pack2(a[2], a[3]), pack2(b[0], b[1]), pack2(b[2], b[3])}; }
; template <class Get, class Epi>
; DI void gemm_loop(int ntiles, int ld, char* shm, const Get& get, const Epi& epi) {
;     ...
;         if (!has_next) break;
;         G_ZERO;
;         cur = nxt; cA = nA; cB = nB; L = Ln;
;         if (wr == 1) BAR;
;     DI void operator()(const AccT& acc, int brow, int bcol, int wr, int wc, int fr, int fq) const {
;     ...
;         EPI_LOOP_ROWS { const size_t row = brow + ai * 128 + wr * 64 + m * 16 + fr; f32x4 o[2];
; #pragma unroll
;             for (int n = 0; n < 2; ++n) { const f32x4 g = acc[ai][0][m][n], u = acc[ai][1][m][n];
; #pragma unroll
;                 for (int j = 0; j < 4; ++j) o[n][j] = silu_f(g[j]) * u[j]; }
;             *(u32x4*)(ACT + row * DFF + col) = pack8(o[0], o[1]); }
	v_rcp_f32_e32 v46, v46
	v_rcp_f32_e32 v47, v47
	v_add_f32_e32 v48, 1.0, v48
	v_add_f32_e32 v49, 1.0, v49
	v_rcp_f32_e32 v48, v48
	v_rcp_f32_e32 v49, v49
	v_pk_mul_f32 v[40:41], v[40:41], v[46:47]
	v_pk_mul_f32 v[38:39], v[44:45], v[38:39]
	v_pk_mul_f32 v[40:41], v[40:41], v[32:33]
	v_pk_mul_f32 v[32:33], v[42:43], v[48:49]
	s_nop 0
	v_pk_mul_f32 v[42:43], v[32:33], v[34:35]
	v_cvt_pk_bf16_f32 v32, v36, v37
	v_mul_f32_e32 v36, 0xbfb8aa3b, v28
	v_cvt_pk_bf16_f32 v33, v38, v39
	v_exp_f32_e32 v38, v36
	v_mul_f32_e32 v36, 0xbfb8aa3b, v29
	v_exp_f32_e32 v39, v36
	v_mad_i64_i32 v[36:37], s[14:15], v50, s46, v[112:113]
	v_cvt_pk_bf16_f32 v34, v40, v41
	v_cvt_pk_bf16_f32 v35, v42, v43
	v_add_f32_e32 v38, 1.0, v38
	v_add_f32_e32 v39, 1.0, v39
	v_lshl_add_u64 v[36:37], v[36:37], 0, v[114:115]
	v_rcp_f32_e32 v38, v38
	v_rcp_f32_e32 v39, v39
	global_store_dwordx4 v[36:37], v[32:35], off sc1
	v_pk_mul_f32 v[28:29], v[28:29], v[38:39]
	s_nop 0
	v_mul_f32_e32 v32, 0xbfb8aa3b, v30
	v_mul_f32_e32 v33, 0xbfb8aa3b, v31
	v_exp_f32_e32 v32, v32
	v_exp_f32_e32 v33, v33
	v_pk_mul_f32 v[20:21], v[28:29], v[20:21]
	v_add_u32_e32 v34, 0xa0, v144
	v_add_f32_e32 v28, 1.0, v32
	v_add_f32_e32 v29, 1.0, v33
	v_mul_f32_e32 v32, 0xbfb8aa3b, v24
	v_mul_f32_e32 v33, 0xbfb8aa3b, v25
	v_rcp_f32_e32 v28, v28
	v_rcp_f32_e32 v29, v29
	v_exp_f32_e32 v32, v32
	v_exp_f32_e32 v33, v33
	v_pk_mul_f32 v[28:29], v[30:31], v[28:29]
	v_add_f32_e32 v30, 1.0, v32
	v_add_f32_e32 v31, 1.0, v33
	v_mul_f32_e32 v32, 0xbfb8aa3b, v26
	v_mul_f32_e32 v33, 0xbfb8aa3b, v27
	v_exp_f32_e32 v32, v32
	v_exp_f32_e32 v33, v33
	v_rcp_f32_e32 v30, v30
	v_rcp_f32_e32 v31, v31
	v_add_f32_e32 v32, 1.0, v32
	v_add_f32_e32 v33, 1.0, v33
	v_rcp_f32_e32 v32, v32
	v_rcp_f32_e32 v33, v33
	v_pk_mul_f32 v[24:25], v[24:25], v[30:31]
	v_pk_mul_f32 v[22:23], v[28:29], v[22:23]
	v_pk_mul_f32 v[24:25], v[24:25], v[16:17]
	v_pk_mul_f32 v[16:17], v[26:27], v[32:33]
	s_nop 0
	v_pk_mul_f32 v[26:27], v[16:17], v[18:19]
	v_cvt_pk_bf16_f32 v16, v20, v21
	v_mul_f32_e32 v20, 0xbfb8aa3b, v12
	v_cvt_pk_bf16_f32 v17, v22, v23
	v_exp_f32_e32 v22, v20
	v_mul_f32_e32 v20, 0xbfb8aa3b, v13
	v_exp_f32_e32 v23, v20
	v_mad_i64_i32 v[20:21], s[14:15], v34, s46, v[112:113]
	v_cvt_pk_bf16_f32 v18, v24, v25
	v_cvt_pk_bf16_f32 v19, v26, v27
	v_add_f32_e32 v22, 1.0, v22
	v_add_f32_e32 v23, 1.0, v23
	v_lshl_add_u64 v[20:21], v[20:21], 0, v[114:115]
	v_rcp_f32_e32 v22, v22
	v_rcp_f32_e32 v23, v23
	global_store_dwordx4 v[20:21], v[16:19], off sc1
	v_pk_mul_f32 v[12:13], v[12:13], v[22:23]
	s_nop 0
	v_mul_f32_e32 v16, 0xbfb8aa3b, v14
	v_mul_f32_e32 v17, 0xbfb8aa3b, v15
	v_exp_f32_e32 v16, v16
	v_exp_f32_e32 v17, v17
	v_pk_mul_f32 v[4:5], v[12:13], v[4:5]
	v_add_u32_e32 v18, 0xb0, v144
	v_add_f32_e32 v12, 1.0, v16
	v_add_f32_e32 v13, 1.0, v17
	v_mul_f32_e32 v16, 0xbfb8aa3b, v8
	v_mul_f32_e32 v17, 0xbfb8aa3b, v9
	v_rcp_f32_e32 v12, v12
	v_rcp_f32_e32 v13, v13
	v_exp_f32_e32 v16, v16
	v_exp_f32_e32 v17, v17
	v_pk_mul_f32 v[12:13], v[14:15], v[12:13]
	v_add_f32_e32 v14, 1.0, v16
	v_add_f32_e32 v15, 1.0, v17
	v_mul_f32_e32 v16, 0xbfb8aa3b, v10
	v_mul_f32_e32 v17, 0xbfb8aa3b, v11
	v_exp_f32_e32 v16, v16
	v_exp_f32_e32 v17, v17
	v_rcp_f32_e32 v14, v14
	v_rcp_f32_e32 v15, v15
	v_add_f32_e32 v16, 1.0, v16
	v_add_f32_e32 v17, 1.0, v17
	v_rcp_f32_e32 v16, v16
	v_rcp_f32_e32 v17, v17
	v_pk_mul_f32 v[8:9], v[8:9], v[14:15]
	v_pk_mul_f32 v[6:7], v[12:13], v[6:7]
	v_pk_mul_f32 v[8:9], v[8:9], v[0:1]
	v_pk_mul_f32 v[0:1], v[10:11], v[16:17]
	s_nop 0
	v_pk_mul_f32 v[10:11], v[0:1], v[2:3]
	v_cvt_pk_bf16_f32 v0, v4, v5
	v_mad_i64_i32 v[4:5], s[14:15], v18, s46, v[112:113]
	v_cvt_pk_bf16_f32 v1, v6, v7
	v_cvt_pk_bf16_f32 v2, v8, v9
	v_cvt_pk_bf16_f32 v3, v10, v11
	v_lshl_add_u64 v[4:5], v[4:5], 0, v[114:115]
	global_store_dwordx4 v[4:5], v[0:3], off sc1
	s_cbranch_vccnz .LBB0_3675
	s_andn2_b64 vcc, exec, s[0:1]
	s_cbranch_vccnz .LBB0_3674
	s_barrier
	s_branch .LBB0_3674
